# P4 epilogue: leading half's alignment barrier moved below its first residual loads
# speedup vs baseline: 1.0049x; 1.0002x over previous
; __device__ __forceinline__ unsigned cvt_pk_bf16(float lo, float hi) { unsigned r; asm volatile("v_cvt_pk_bf16_f32 %0, %1, %2" : "=v"(r) : "v"(lo), "v"(hi)); return r; }
; #define PG8_BAR __builtin_amdgcn_s_barrier()
;     __device__ __forceinline__ void operator()(const f32x4 (&acc)[2][2][4][2], const Unit& u, int wr, int wc, int fr, int fq) const {
;     ...
;                     for (int bj = 0; bj < 2; ++bj) { const size_t off = (size_t)(row0 + ai * HALF + (2 * mh + ml) * 16) * 1024 + col0 + bj * HALF;
;                         bv[ml][bj][0] = *(const f32x4*)(base + off); bv[ml][bj][1] = *(const f32x4*)(base + off + 4); }
;                 asm volatile("" ::: "memory");
; #pragma unroll
;                 for (int ml = 0; ml < 2; ++ml) { const int m = 2 * mh + ml; const int row = row0 + ai * HALF + m * 16; float s = 0.f;
; #pragma unroll
;                     for (int bj = 0; bj < 2; ++bj) { const size_t off = (size_t)row * 1024 + col0 + bj * HALF;
;                         const f32x4 v0 = bv[ml][bj][0] + acc[ai][bj][m][0], v1 = bv[ml][bj][1] + acc[ai][bj][m][1];
;                         *(f32x4*)(out + off) = v0; *(f32x4*)(out + off + 4) = v1;
;                         u32x4 w; w.x = cvt_pk_bf16(v0[0], v0[1]); w.y = cvt_pk_bf16(v0[2], v0[3]); w.z = cvt_pk_bf16(v1[0], v1[1]); w.w = cvt_pk_bf16(v1[2], v1[3]);
;                         if (xb) *(u32x4*)(xb + off) = w;
; template <class Epi, class Sched, bool ALIGN_EPI = false, bool SP2 = false>
; __device__ __forceinline__ void gemm_phase(PG8_LAS unsigned char* lds, const Gemm g, const Sched& S, const Epi& E) {
;     ...
;         if constexpr (ALIGN_EPI) { if (wr == 0) PG8_BAR; }
.LBB0_540:
	v_lshl_add_u32 v172, s13, 8, v180
	v_lshl_or_b32 v168, s12, 8, v182
	v_ashrrev_i32_e32 v169, 31, v168
	v_ashrrev_i32_e32 v173, 31, v172
	v_lshl_add_u64 v[170:171], v[168:169], 2, v[156:157]
	v_lshlrev_b64 v[128:129], 12, v[172:173]
	v_or_b32_e32 v174, 16, v172
	v_lshl_add_u64 v[128:129], v[170:171], 0, v[128:129]
	v_ashrrev_i32_e32 v175, 31, v174
	global_load_dwordx4 v[152:155], v[128:129], off offset:16
	global_load_dwordx4 v[176:179], v[128:129], off
	global_load_dwordx4 v[144:147], v[128:129], off offset:528
	global_load_dwordx4 v[148:151], v[128:129], off offset:512
	v_lshlrev_b64 v[128:129], 12, v[174:175]
	v_lshl_add_u64 v[132:133], v[170:171], 0, v[128:129]
	global_load_dwordx4 v[136:139], v[132:133], off offset:16
	global_load_dwordx4 v[140:143], v[132:133], off
	global_load_dwordx4 v[128:131], v[132:133], off offset:528
	s_nop 0
	global_load_dwordx4 v[132:135], v[132:133], off offset:512
	v_lshlrev_b64 v[184:185], 10, v[172:173]
	v_lshl_add_u64 v[184:185], v[184:185], 0, v[168:169]
	s_and_b64 vcc, exec, s[22:23]
	s_cbranch_vccz .Lp4_nobar
	s_barrier
.Lp4_nobar:
	s_andn2_b64 vcc, exec, s[24:25]
	s_waitcnt vmcnt(0)
	v_pk_add_f32 v[122:123], v[122:123], v[154:155]
	v_pk_add_f32 v[126:127], v[126:127], v[178:179]
	v_cndmask_b32_e64 v178, 0, 1, s[24:25]
	v_pk_add_f32 v[124:125], v[124:125], v[176:177]
	v_pk_add_f32 v[120:121], v[120:121], v[152:153]
	v_lshl_add_u64 v[176:177], v[184:185], 2, s[10:11]
	v_cmp_ne_u32_e64 s[6:7], 1, v178
	v_lshl_add_u64 v[178:179], v[184:185], 1, s[18:19]
	global_store_dwordx4 v[176:177], v[124:127], off
	global_store_dwordx4 v[176:177], v[120:123], off offset:16
	v_cvt_pk_bf16_f32 v152, v124, v125
	v_cvt_pk_bf16_f32 v153, v126, v127
	v_cvt_pk_bf16_f32 v154, v120, v121
	v_cvt_pk_bf16_f32 v155, v122, v123
	s_cbranch_vccnz .LBB0_542
	global_store_dwordx4 v[178:179], v[152:155], off
